# seam before the q|k|gate GEMM: the agent-scope invalidate is issued right after the workgroup's own arrival (it loads nothing while it waits), overlapping the wait instead of following it
# speedup vs baseline: 1.0073x; 1.0073x over previous
; __device__ __forceinline__ unsigned xb_ld(unsigned* p)              { return __hip_atomic_load(p, __ATOMIC_RELAXED, __HIP_MEMORY_SCOPE_AGENT); }
; #define XB_SPIN(cond, bar) do { unsigned _sp = 0; while (cond) { __builtin_amdgcn_s_sleep(1); \
;     if ((++_sp & 255u) == 0u) { if (xb_ld(&(bar)[XB_TMO])) break; if (_sp > XB_SPIN_CAP) { atomicAdd(&(bar)[XB_TMO], 1u); break; } } } } while (0)
; __device__ __forceinline__ void xcd_barrier(const XcdBarrier& b) {
;     ...
;         } else {
;             XB_SPIN(xb_ld(&bar[XB_XGEN(b.x)]) == gen, bar);
;             __builtin_amdgcn_fence(__ATOMIC_ACQUIRE, "agent");
;             asm volatile("s_waitcnt vmcnt(0)" ::: "memory");
.Lmy_bar_poll_3:
	buffer_inv sc1
	v_mov_b32_e32 v3, 0x3000
	s_mov_b32 s97, 0

; __device__ __forceinline__ unsigned xb_ld(unsigned* p)              { return __hip_atomic_load(p, __ATOMIC_RELAXED, __HIP_MEMORY_SCOPE_AGENT); }
; __device__ __forceinline__ unsigned xb_add(unsigned* p, unsigned v) { return __hip_atomic_fetch_add(p, v, __ATOMIC_RELAXED, __HIP_MEMORY_SCOPE_AGENT); }
; #define XB_SPIN(cond, bar) do { unsigned _sp = 0; while (cond) { __builtin_amdgcn_s_sleep(1); \
;     if ((++_sp & 255u) == 0u) { if (xb_ld(&(bar)[XB_TMO])) break; if (_sp > XB_SPIN_CAP) { atomicAdd(&(bar)[XB_TMO], 1u); break; } } } } while (0)
;     __host__ __device__ bool next(int i, Unit& u) const {
;         const long L = (long)i * G + c; if (L >= nwg) return false;
;         int wgid = (int)L; { const int q = nwg / NXCD, r = nwg % NXCD, xcd = wgid % NXCD, off = wgid / NXCD; wgid = (xcd < r ? xcd * (q + 1) : r * (q + 1) + (xcd - r) * q) + off; }
;         const int nig = WGM * nN, gid = wgid / nig, fm = gid * WGM, gsz = (nM - fm) < WGM ? (nM - fm) : WGM;
;         u.pm = fm + ((wgid % nig) % gsz); u.pn = (wgid % nig) / gsz; return true;
; __device__ __forceinline__ void xcd_barrier(const XcdBarrier& b) {
;     ...
;             __builtin_amdgcn_fence(__ATOMIC_ACQUIRE, "agent");
;             xb_add(&bar[XB_XGEN(b.x)], 1u);
;             asm volatile("s_waitcnt vmcnt(0)" ::: "memory");
;         } else {
;             XB_SPIN(xb_ld(&bar[XB_XGEN(b.x)]) == gen, bar);
;             __builtin_amdgcn_fence(__ATOMIC_ACQUIRE, "agent");
;             asm volatile("s_waitcnt vmcnt(0)" ::: "memory");
;         }
;     }
;     __syncthreads();
.Lmy_bar_go_3:
.LBB0_477:
	s_or_b64 exec, exec, s[4:5]
	s_waitcnt lgkmcnt(0)
	s_barrier
.LBB0_478:
	s_cmp_lt_i32 s56, 6
	s_cselect_b64 s[4:5], -1, 0
	s_and_b64 s[6:7], s[4:5], s[2:3]
	s_andn2_b64 vcc, exec, s[6:7]
	s_cbranch_vccnz .LBB0_581
	s_cmpk_lt_i32 s33, 0x300
	s_cselect_b64 s[2:3], -1, 0
	s_cmpk_gt_i32 s33, 0x2ff
	v_readfirstlane_b32 s14, v184
	s_cbranch_scc1 .LBB0_481
	s_ashr_i32 s4, s33, 31
	s_lshr_b32 s4, s4, 29
	s_add_i32 s4, s33, s4
	s_ashr_i32 s5, s4, 3
	s_and_b32 s4, s4, -8
	s_sub_i32 s4, s33, s4
	s_cmp_lt_i32 s4, 0
	s_movk_i32 s8, 0x61
	s_cselect_b32 s8, s8, 0x60
	s_mul_i32 s4, s4, s8
	s_add_i32 s4, s4, s5
	s_mul_hi_i32 s5, s4, 0x2aaaaaab
	s_lshr_b32 s8, s5, 31
	s_ashr_i32 s5, s5, 4
	s_add_i32 s5, s5, s8
	s_lshl_b32 s8, s5, 3
	s_mulk_i32 s5, 0x60
	s_sub_i32 s4, s4, s5
	s_bfe_i32 s5, s4, 0x80000
	s_bfe_u32 s5, s5, 0x3000c
	s_add_i32 s5, s4, s5
	s_bfe_i32 s9, s5, 0x80000
	s_and_b32 s5, s5, 0xf8
	s_sub_i32 s4, s4, s5
	s_sext_i32_i16 s9, s9
	s_sext_i32_i8 s4, s4
	s_add_i32 s24, s8, s4
	s_ashr_i32 s4, s9, 3

; __device__ __forceinline__ unsigned xb_ld(unsigned* p)              { return __hip_atomic_load(p, __ATOMIC_RELAXED, __HIP_MEMORY_SCOPE_AGENT); }
; __device__ __forceinline__ unsigned xb_add(unsigned* p, unsigned v) { return __hip_atomic_fetch_add(p, v, __ATOMIC_RELAXED, __HIP_MEMORY_SCOPE_AGENT); }
; #define XB_SPIN(cond, bar) do { unsigned _sp = 0; while (cond) { __builtin_amdgcn_s_sleep(1); \
;     if ((++_sp & 255u) == 0u) { if (xb_ld(&(bar)[XB_TMO])) break; if (_sp > XB_SPIN_CAP) { atomicAdd(&(bar)[XB_TMO], 1u); break; } } } } while (0)
; __device__ __forceinline__ void final_norm(const Ptrs& P, int gw, int NGW, int lane) {
;     const float* ssq2 = (const float*)(P.ws + WS_SSQ2);
;     f32x4 g[4];
; #pragma unroll
;     for (int j = 0; j < 4; ++j) g[j] = ((const f32x4*)P.fng)[lane + 64 * j];
;     for (int m = gw; m < M; m += NGW) { f32x4* xr = (f32x4*)(P.out + (size_t)m * D) + lane;
;         const float rs = __builtin_amdgcn_rsqf(ssq2[m] * (1.0f / 1024.0f) + 1e-6f);
; #pragma unroll
;         for (int j = 0; j < 4; ++j) { const f32x4 v = xr[64 * j]; xr[64 * j] = v * rs * g[j]; } }
; __device__ __forceinline__ void xcd_barrier(const XcdBarrier& b) {
;     ...
;             __builtin_amdgcn_fence(__ATOMIC_ACQUIRE, "agent");
;             xb_add(&bar[XB_XGEN(b.x)], 1u);
;             asm volatile("s_waitcnt vmcnt(0)" ::: "memory");
;         } else {
;             XB_SPIN(xb_ld(&bar[XB_XGEN(b.x)]) == gen, bar);
;             __builtin_amdgcn_fence(__ATOMIC_ACQUIRE, "agent");
;             asm volatile("s_waitcnt vmcnt(0)" ::: "memory");
;         }
;     }
;     __syncthreads();
.Lmy_bar_go_6:
.LBB0_788:
	s_or_b64 exec, exec, s[2:3]
	s_cmpk_gt_i32 s60, 0x3fff
	s_waitcnt lgkmcnt(0)
	s_barrier
	s_cbranch_scc1 .LBB0_791
	v_lshlrev_b32_e32 v16, 4, v232
	global_load_dwordx4 v[0:3], v16, s[40:41]
	global_load_dwordx4 v[4:7], v16, s[40:41] offset:1024
	global_load_dwordx4 v[8:11], v16, s[40:41] offset:2048
	global_load_dwordx4 v[12:15], v16, s[40:41] offset:3072
	s_ashr_i32 s61, s60, 31
	s_lshl_b64 s[0:1], s[60:61], 2
	s_add_u32 s0, s54, s0
	s_addc_u32 s1, s55, s1
	s_add_u32 s0, s0, 0x120000
	s_addc_u32 s1, s1, 0
	s_ashr_i32 s63, s62, 31
	s_lshl_b64 s[2:3], s[62:63], 2
	s_lshl_b64 s[4:5], s[60:61], 12
	s_add_u32 s4, s52, s4
	v_mov_b32_e32 v17, 0
	s_addc_u32 s5, s53, s5
	v_lshl_add_u64 v[18:19], s[4:5], 0, v[16:17]
	s_mov_b64 s[4:5], 0xc00
	v_lshl_add_u64 v[18:19], v[18:19], 0, s[4:5]
	s_lshl_b64 s[4:5], s[62:63], 12
	v_mov_b32_e32 v16, 0x358637bd
